# GEMM1 K-loop: reversed s_setprio polarity (load segments prio 1, MFMA clusters prio 0), redundant flip pairs dropped; + no entry grid.sync
# speedup vs baseline: 1.0048x; 1.0048x over previous
; #define PG8_STAGE(bufoff, gbase, voff) do { _Pragma("unroll") for (int _i = 0; _i < 2; ++_i) \
;         __builtin_amdgcn_global_load_lds((const unsigned*)((const char*)(gbase) + (voff)[_i]), (PG8_LAS unsigned*)(lds + (bufoff) + ldsw + _i * 8192), 16, 0, 0); } while (0)
; #define PG8_LDA(dst, b, h) do { _Pragma("unroll") for (int m = 0; m < 4; ++m) _Pragma("unroll") for (int k = 0; k < 2; ++k) dst[m][k] = *(const PG8_LAS bf16x8*)(lds + PG8_SA(b, h) + aoff + m * 2048 + k * 1024); } while (0)
; #define PG8_LDB(dst, b, h) do { _Pragma("unroll") for (int n = 0; n < 2; ++n) _Pragma("unroll") for (int k = 0; k < 2; ++k) dst[n][k] = *(const PG8_LAS bf16x8*)(lds + PG8_SB(b, h) + boff + n * 2048 + k * 1024); } while (0)
; #define PG8_MMA(ai, bj, At, Bt) do { __builtin_amdgcn_s_setprio(1); _Pragma("unroll") for (int m = 0; m < 4; ++m) _Pragma("unroll") for (int n = 0; n < 2; ++n) _Pragma("unroll") for (int k = 0; k < 2; ++k) \
;         acc[ai][bj][m][n] = __builtin_amdgcn_mfma_f32_16x16x32_bf16(Bt[n][k], At[m][k], acc[ai][bj][m][n], 0, 0, 0); __builtin_amdgcn_s_setprio(0); } while (0)
; #define PG8_WAIT_V(n) asm volatile("s_waitcnt vmcnt(" #n ")" ::: "memory")
; #define PG8_WAIT_L(n) asm volatile("s_waitcnt lgkmcnt(" #n ")" ::: "memory")
; #define PG8_BAR __builtin_amdgcn_s_barrier()
; #define PG8_SCHED __builtin_amdgcn_sched_barrier(0)
; template <class Epi, class Sched, bool ALIGN_EPI = false, bool SP2 = false>
; __device__ __forceinline__ void gemm_phase(PG8_LAS unsigned char* lds, const Gemm g, const Sched& S, const Epi& E) {
;     ...
;             PG8_LDB(B0, 0, 0); PG8_LDB(B1, 0, 1); PG8_SCHED; PG8_LDA(At, 0, 0); PG8_STAGE(PG8_SA(1, 1), a1 + hstep, voffA);
;             PG8_WAIT_V(8); PG8_WAIT_L(0); PG8_BAR; PG8_MMA(0, 0, At, B0); PG8_MMA(0, 1, At, B1); PG8_BAR; PG8_SCHED;
;             PG8_LDA(At, 0, 1); PG8_STAGE(PG8_SB(0, 0), b2, voffB); PG8_STAGE(PG8_SB(0, 1), b2 + hstep, voffB); PG8_STAGE(PG8_SA(0, 0), a2, voffA);
;             PG8_WAIT_V(8); PG8_WAIT_L(0); PG8_BAR; PG8_MMA(1, 0, At, B0); PG8_MMA(1, 1, At, B1); PG8_BAR; PG8_SCHED;
.LBB0_399:
	v_or_b32_e32 v142, 0x10000, v141
	v_add_u32_e32 v146, 0x10400, v141
	v_add_u32_e32 v150, 0x10800, v141
	v_add_u32_e32 v154, 0x10c00, v141
	v_or_b32_e32 v158, 0x14000, v141
	v_add_u32_e32 v162, 0x14400, v141
	v_add_u32_e32 v166, 0x14800, v141
	v_add_u32_e32 v170, 0x14c00, v141
	s_add_i32 s74, s62, 2
	ds_read_b128 v[142:145], v142
	ds_read_b128 v[146:149], v146
	ds_read_b128 v[150:153], v150
	ds_read_b128 v[154:157], v154
	ds_read_b128 v[158:161], v158
	ds_read_b128 v[162:165], v162
	ds_read_b128 v[166:169], v166
	ds_read_b128 v[170:173], v170
	s_add_u32 s75, s60, 0x80
	s_addc_u32 s63, s61, 0
	s_cmp_eq_u32 s68, s62
	s_cselect_b32 s62, s40, s75
	s_cselect_b32 s63, s41, s63
	s_cselect_b32 s77, s53, s73
	s_cselect_b32 s76, s52, s55
	v_lshl_add_u64 v[210:211], s[60:61], 0, v[136:137]
	s_add_i32 m0, s12, 0xc000
	ds_read_b128 v[174:177], v140
	ds_read_b128 v[178:181], v140 offset:1024
	ds_read_b128 v[182:185], v140 offset:2048
	ds_read_b128 v[186:189], v140 offset:3072
	ds_read_b128 v[190:193], v140 offset:4096
	ds_read_b128 v[202:205], v140 offset:5120
	ds_read_b128 v[206:209], v140 offset:6144
	ds_read_b128 v[230:233], v140 offset:7168
	global_load_lds_dwordx4 v[210:211], off
	v_lshl_add_u64 v[210:211], s[60:61], 0, v[138:139]
	s_add_i32 m0, s12, 0xe000
	s_nop 0
	global_load_lds_dwordx4 v[210:211], off
	s_waitcnt vmcnt(8)
	s_waitcnt lgkmcnt(0)
	s_barrier
	s_setprio 0
	s_waitcnt lgkmcnt(0)
	v_mfma_f32_16x16x32_bf16 v[126:129], v[142:145], v[174:177], v[126:129]
	v_mfma_f32_16x16x32_bf16 v[122:125], v[150:153], v[174:177], v[122:125]
	v_mfma_f32_16x16x32_bf16 v[118:121], v[142:145], v[182:185], v[118:121]
	v_mfma_f32_16x16x32_bf16 v[114:117], v[150:153], v[182:185], v[114:117]
	v_mfma_f32_16x16x32_bf16 v[110:113], v[142:145], v[190:193], v[110:113]
	v_mfma_f32_16x16x32_bf16 v[106:109], v[150:153], v[190:193], v[106:109]
	v_mfma_f32_16x16x32_bf16 v[102:105], v[142:145], v[206:209], v[102:105]
	v_mfma_f32_16x16x32_bf16 v[98:101], v[150:153], v[206:209], v[98:101]
	v_mfma_f32_16x16x32_bf16 v[126:129], v[146:149], v[178:181], v[126:129]
	v_mfma_f32_16x16x32_bf16 v[122:125], v[154:157], v[178:181], v[122:125]
	v_mfma_f32_16x16x32_bf16 v[118:121], v[146:149], v[186:189], v[118:121]
	v_mfma_f32_16x16x32_bf16 v[114:117], v[154:157], v[186:189], v[114:117]
	v_mfma_f32_16x16x32_bf16 v[110:113], v[146:149], v[202:205], v[110:113]
	v_mfma_f32_16x16x32_bf16 v[106:109], v[154:157], v[202:205], v[106:109]
	v_mfma_f32_16x16x32_bf16 v[102:105], v[146:149], v[230:233], v[102:105]
	v_mfma_f32_16x16x32_bf16 v[98:101], v[154:157], v[230:233], v[98:101]
	v_mfma_f32_16x16x32_bf16 v[68:71], v[158:161], v[174:177], v[68:71]
	v_mfma_f32_16x16x32_bf16 v[64:67], v[166:169], v[174:177], v[64:67]
	v_mfma_f32_16x16x32_bf16 v[60:63], v[158:161], v[182:185], v[60:63]
	v_mfma_f32_16x16x32_bf16 v[56:59], v[166:169], v[182:185], v[56:59]
	v_mfma_f32_16x16x32_bf16 v[52:55], v[158:161], v[190:193], v[52:55]
	v_mfma_f32_16x16x32_bf16 v[48:51], v[166:169], v[190:193], v[48:51]
	v_mfma_f32_16x16x32_bf16 v[44:47], v[158:161], v[206:209], v[44:47]
	v_mfma_f32_16x16x32_bf16 v[40:43], v[166:169], v[206:209], v[40:43]
	v_mfma_f32_16x16x32_bf16 v[68:71], v[162:165], v[178:181], v[68:71]
	v_mfma_f32_16x16x32_bf16 v[64:67], v[170:173], v[178:181], v[64:67]
	v_mfma_f32_16x16x32_bf16 v[60:63], v[162:165], v[186:189], v[60:63]
	v_mfma_f32_16x16x32_bf16 v[56:59], v[170:173], v[186:189], v[56:59]
	v_mfma_f32_16x16x32_bf16 v[52:55], v[162:165], v[202:205], v[52:55]
	v_mfma_f32_16x16x32_bf16 v[48:51], v[170:173], v[202:205], v[48:51]
	v_mfma_f32_16x16x32_bf16 v[44:47], v[162:165], v[230:233], v[44:47]
	v_mfma_f32_16x16x32_bf16 v[40:43], v[170:173], v[230:233], v[40:43]
	s_setprio 1
	s_barrier
	s_mov_b32 m0, s13
	v_lshl_add_u64 v[210:211], s[76:77], 0, v[96:97]
	v_lshl_add_u64 v[234:235], s[76:77], 0, v[130:131]
	s_add_u32 s76, s76, s42
	ds_read_b128 v[174:177], v140 offset:16384
	ds_read_b128 v[178:181], v140 offset:17408
	ds_read_b128 v[182:185], v140 offset:18432
	ds_read_b128 v[186:189], v140 offset:19456
	ds_read_b128 v[190:193], v140 offset:20480
	ds_read_b128 v[202:205], v140 offset:21504
	ds_read_b128 v[206:209], v140 offset:22528
	ds_read_b128 v[230:233], v140 offset:23552
	global_load_lds_dwordx4 v[210:211], off
	s_mov_b32 m0, s16
	s_addc_u32 s77, s77, s43
	global_load_lds_dwordx4 v[234:235], off
	v_lshl_add_u64 v[236:237], s[76:77], 0, v[96:97]
	s_mov_b32 m0, s17
	v_lshl_add_u64 v[238:239], s[76:77], 0, v[130:131]
	global_load_lds_dwordx4 v[236:237], off
	s_mov_b32 m0, s20
	v_lshl_add_u64 v[240:241], s[62:63], 0, v[134:135]
	global_load_lds_dwordx4 v[238:239], off
	s_mov_b32 m0, s12
	v_lshl_add_u64 v[242:243], s[62:63], 0, v[132:133]
	global_load_lds_dwordx4 v[240:241], off
	s_mov_b32 m0, s21
	s_nop 0
	global_load_lds_dwordx4 v[242:243], off
	s_waitcnt vmcnt(8)
	s_waitcnt lgkmcnt(0)
	s_barrier
; #define PG8_STAGE(bufoff, gbase, voff) do { _Pragma("unroll") for (int _i = 0; _i < 2; ++_i) \
;         __builtin_amdgcn_global_load_lds((const unsigned*)((const char*)(gbase) + (voff)[_i]), (PG8_LAS unsigned*)(lds + (bufoff) + ldsw + _i * 8192), 16, 0, 0); } while (0)
; #define PG8_LDA(dst, b, h) do { _Pragma("unroll") for (int m = 0; m < 4; ++m) _Pragma("unroll") for (int k = 0; k < 2; ++k) dst[m][k] = *(const PG8_LAS bf16x8*)(lds + PG8_SA(b, h) + aoff + m * 2048 + k * 1024); } while (0)
; #define PG8_LDB(dst, b, h) do { _Pragma("unroll") for (int n = 0; n < 2; ++n) _Pragma("unroll") for (int k = 0; k < 2; ++k) dst[n][k] = *(const PG8_LAS bf16x8*)(lds + PG8_SB(b, h) + boff + n * 2048 + k * 1024); } while (0)
; #define PG8_MMA(ai, bj, At, Bt) do { __builtin_amdgcn_s_setprio(1); _Pragma("unroll") for (int m = 0; m < 4; ++m) _Pragma("unroll") for (int n = 0; n < 2; ++n) _Pragma("unroll") for (int k = 0; k < 2; ++k) \
;         acc[ai][bj][m][n] = __builtin_amdgcn_mfma_f32_16x16x32_bf16(Bt[n][k], At[m][k], acc[ai][bj][m][n], 0, 0, 0); __builtin_amdgcn_s_setprio(0); } while (0)
; #define PG8_WAIT_V(n) asm volatile("s_waitcnt vmcnt(" #n ")" ::: "memory")
; #define PG8_WAIT_L(n) asm volatile("s_waitcnt lgkmcnt(" #n ")" ::: "memory")
; #define PG8_BAR __builtin_amdgcn_s_barrier()
; #define PG8_SCHED __builtin_amdgcn_sched_barrier(0)
; template <class Epi, class Sched, bool ALIGN_EPI = false, bool SP2 = false>
; __device__ __forceinline__ void gemm_phase(PG8_LAS unsigned char* lds, const Gemm g, const Sched& S, const Epi& E) {
;     ...
;             PG8_WAIT_V(8); PG8_WAIT_L(0); PG8_BAR; PG8_MMA(1, 0, At, B0); PG8_MMA(1, 1, At, B1); PG8_BAR; PG8_SCHED;
;             PG8_LDB(B0, 1, 0); PG8_LDB(B1, 1, 1); PG8_SCHED; PG8_LDA(At, 1, 0); PG8_STAGE(PG8_SA(0, 1), a2 + hstep, voffA);
;             PG8_WAIT_V(8); PG8_WAIT_L(0); PG8_BAR; PG8_MMA(0, 0, At, B0); PG8_MMA(0, 1, At, B1); PG8_BAR; PG8_SCHED;
	s_setprio 0
	s_waitcnt lgkmcnt(0)
	v_mfma_f32_16x16x32_bf16 v[92:95], v[142:145], v[174:177], v[92:95]
	v_mfma_f32_16x16x32_bf16 v[88:91], v[150:153], v[174:177], v[88:91]
	v_mfma_f32_16x16x32_bf16 v[84:87], v[142:145], v[182:185], v[84:87]
	v_mfma_f32_16x16x32_bf16 v[80:83], v[150:153], v[182:185], v[80:83]
	v_mfma_f32_16x16x32_bf16 v[76:79], v[142:145], v[190:193], v[76:79]
	v_mfma_f32_16x16x32_bf16 v[72:75], v[150:153], v[190:193], v[72:75]
	v_mfma_f32_16x16x32_bf16 v[12:15], v[142:145], v[206:209], v[12:15]
	v_mfma_f32_16x16x32_bf16 v[8:11], v[150:153], v[206:209], v[8:11]
	v_mfma_f32_16x16x32_bf16 v[92:95], v[146:149], v[178:181], v[92:95]
	v_mfma_f32_16x16x32_bf16 v[88:91], v[154:157], v[178:181], v[88:91]
	v_mfma_f32_16x16x32_bf16 v[84:87], v[146:149], v[186:189], v[84:87]
	v_mfma_f32_16x16x32_bf16 v[80:83], v[154:157], v[186:189], v[80:83]
	v_mfma_f32_16x16x32_bf16 v[76:79], v[146:149], v[202:205], v[76:79]
	v_mfma_f32_16x16x32_bf16 v[72:75], v[154:157], v[202:205], v[72:75]
	v_mfma_f32_16x16x32_bf16 v[12:15], v[146:149], v[230:233], v[12:15]
	v_mfma_f32_16x16x32_bf16 v[8:11], v[154:157], v[230:233], v[8:11]
	v_mfma_f32_16x16x32_bf16 v[36:39], v[158:161], v[174:177], v[36:39]
	v_mfma_f32_16x16x32_bf16 v[32:35], v[166:169], v[174:177], v[32:35]
	v_mfma_f32_16x16x32_bf16 v[28:31], v[158:161], v[182:185], v[28:31]
	v_mfma_f32_16x16x32_bf16 v[24:27], v[166:169], v[182:185], v[24:27]
	v_mfma_f32_16x16x32_bf16 v[20:23], v[158:161], v[190:193], v[20:23]
	v_mfma_f32_16x16x32_bf16 v[16:19], v[166:169], v[190:193], v[16:19]
	v_mfma_f32_16x16x32_bf16 v[4:7], v[158:161], v[206:209], v[4:7]
	v_mfma_f32_16x16x32_bf16 v[0:3], v[166:169], v[206:209], v[0:3]
	v_mfma_f32_16x16x32_bf16 v[36:39], v[162:165], v[178:181], v[36:39]
	v_mfma_f32_16x16x32_bf16 v[32:35], v[170:173], v[178:181], v[32:35]
	v_mfma_f32_16x16x32_bf16 v[28:31], v[162:165], v[186:189], v[28:31]
	v_mfma_f32_16x16x32_bf16 v[24:27], v[170:173], v[186:189], v[24:27]
	v_mfma_f32_16x16x32_bf16 v[20:23], v[162:165], v[202:205], v[20:23]
	v_mfma_f32_16x16x32_bf16 v[16:19], v[170:173], v[202:205], v[16:19]
	v_mfma_f32_16x16x32_bf16 v[4:7], v[162:165], v[230:233], v[4:7]
	v_mfma_f32_16x16x32_bf16 v[0:3], v[170:173], v[230:233], v[0:3]
	s_setprio 1
	s_barrier
	v_or_b32_e32 v142, 0x18000, v141
	v_add_u32_e32 v146, 0x18400, v141
	v_add_u32_e32 v150, 0x18800, v141
	v_add_u32_e32 v154, 0x18c00, v141
	v_or_b32_e32 v158, 0x1c000, v141
	v_add_u32_e32 v162, 0x1c400, v141
	v_add_u32_e32 v166, 0x1c800, v141
	v_add_u32_e32 v170, 0x1cc00, v141
	ds_read_b128 v[142:145], v142
	ds_read_b128 v[146:149], v146
	ds_read_b128 v[150:153], v150
	ds_read_b128 v[154:157], v154
	ds_read_b128 v[158:161], v158
	ds_read_b128 v[162:165], v162
	ds_read_b128 v[166:169], v166
	ds_read_b128 v[170:173], v170
	s_add_u32 s62, s62, s42
	s_addc_u32 s63, s63, s43
	s_mov_b32 m0, s22
	v_lshl_add_u64 v[244:245], s[62:63], 0, v[134:135]
	ds_read_b128 v[174:177], v140 offset:32768
	ds_read_b128 v[178:181], v140 offset:33792
	ds_read_b128 v[182:185], v140 offset:34816
	ds_read_b128 v[186:189], v140 offset:35840
	ds_read_b128 v[190:193], v140 offset:36864
	ds_read_b128 v[202:205], v140 offset:37888
	ds_read_b128 v[206:209], v140 offset:38912
	ds_read_b128 v[230:233], v140 offset:39936
	global_load_lds_dwordx4 v[244:245], off
	v_lshl_add_u64 v[244:245], s[62:63], 0, v[132:133]
	s_mov_b32 m0, s23
	s_nop 0
	global_load_lds_dwordx4 v[244:245], off
	s_waitcnt vmcnt(8)
	s_waitcnt lgkmcnt(0)
	s_barrier
	s_setprio 0
	s_waitcnt lgkmcnt(0)
	v_mfma_f32_16x16x32_bf16 v[126:129], v[142:145], v[174:177], v[126:129]
	v_mfma_f32_16x16x32_bf16 v[122:125], v[150:153], v[174:177], v[122:125]
	v_mfma_f32_16x16x32_bf16 v[118:121], v[142:145], v[182:185], v[118:121]
	v_mfma_f32_16x16x32_bf16 v[114:117], v[150:153], v[182:185], v[114:117]
	v_mfma_f32_16x16x32_bf16 v[110:113], v[142:145], v[190:193], v[110:113]
	v_mfma_f32_16x16x32_bf16 v[106:109], v[150:153], v[190:193], v[106:109]
	v_mfma_f32_16x16x32_bf16 v[102:105], v[142:145], v[206:209], v[102:105]
	v_mfma_f32_16x16x32_bf16 v[98:101], v[150:153], v[206:209], v[98:101]
	v_mfma_f32_16x16x32_bf16 v[126:129], v[146:149], v[178:181], v[126:129]
	v_mfma_f32_16x16x32_bf16 v[122:125], v[154:157], v[178:181], v[122:125]
	v_mfma_f32_16x16x32_bf16 v[118:121], v[146:149], v[186:189], v[118:121]
	v_mfma_f32_16x16x32_bf16 v[114:117], v[154:157], v[186:189], v[114:117]
	v_mfma_f32_16x16x32_bf16 v[110:113], v[146:149], v[202:205], v[110:113]
	v_mfma_f32_16x16x32_bf16 v[106:109], v[154:157], v[202:205], v[106:109]
	v_mfma_f32_16x16x32_bf16 v[102:105], v[146:149], v[230:233], v[102:105]
	v_mfma_f32_16x16x32_bf16 v[98:101], v[154:157], v[230:233], v[98:101]
	v_mfma_f32_16x16x32_bf16 v[68:71], v[158:161], v[174:177], v[68:71]
	v_mfma_f32_16x16x32_bf16 v[64:67], v[166:169], v[174:177], v[64:67]
	v_mfma_f32_16x16x32_bf16 v[60:63], v[158:161], v[182:185], v[60:63]
	v_mfma_f32_16x16x32_bf16 v[56:59], v[166:169], v[182:185], v[56:59]
	v_mfma_f32_16x16x32_bf16 v[52:55], v[158:161], v[190:193], v[52:55]
	v_mfma_f32_16x16x32_bf16 v[48:51], v[166:169], v[190:193], v[48:51]
	v_mfma_f32_16x16x32_bf16 v[44:47], v[158:161], v[206:209], v[44:47]
	v_mfma_f32_16x16x32_bf16 v[40:43], v[166:169], v[206:209], v[40:43]
	v_mfma_f32_16x16x32_bf16 v[68:71], v[162:165], v[178:181], v[68:71]
	v_mfma_f32_16x16x32_bf16 v[64:67], v[170:173], v[178:181], v[64:67]
	v_mfma_f32_16x16x32_bf16 v[60:63], v[162:165], v[186:189], v[60:63]
	v_mfma_f32_16x16x32_bf16 v[56:59], v[170:173], v[186:189], v[56:59]
	v_mfma_f32_16x16x32_bf16 v[52:55], v[162:165], v[202:205], v[52:55]
	v_mfma_f32_16x16x32_bf16 v[48:51], v[170:173], v[202:205], v[48:51]
	v_mfma_f32_16x16x32_bf16 v[44:47], v[162:165], v[230:233], v[44:47]
	v_mfma_f32_16x16x32_bf16 v[40:43], v[170:173], v[230:233], v[40:43]
	s_setprio 1
	s_barrier
; #define PG8_STAGE(bufoff, gbase, voff) do { _Pragma("unroll") for (int _i = 0; _i < 2; ++_i) \
;         __builtin_amdgcn_global_load_lds((const unsigned*)((const char*)(gbase) + (voff)[_i]), (PG8_LAS unsigned*)(lds + (bufoff) + ldsw + _i * 8192), 16, 0, 0); } while (0)
; #define PG8_LDA(dst, b, h) do { _Pragma("unroll") for (int m = 0; m < 4; ++m) _Pragma("unroll") for (int k = 0; k < 2; ++k) dst[m][k] = *(const PG8_LAS bf16x8*)(lds + PG8_SA(b, h) + aoff + m * 2048 + k * 1024); } while (0)
; #define PG8_MMA(ai, bj, At, Bt) do { __builtin_amdgcn_s_setprio(1); _Pragma("unroll") for (int m = 0; m < 4; ++m) _Pragma("unroll") for (int n = 0; n < 2; ++n) _Pragma("unroll") for (int k = 0; k < 2; ++k) \
;         acc[ai][bj][m][n] = __builtin_amdgcn_mfma_f32_16x16x32_bf16(Bt[n][k], At[m][k], acc[ai][bj][m][n], 0, 0, 0); __builtin_amdgcn_s_setprio(0); } while (0)
; #define PG8_WAIT_V(n) asm volatile("s_waitcnt vmcnt(" #n ")" ::: "memory")
; #define PG8_WAIT_L(n) asm volatile("s_waitcnt lgkmcnt(" #n ")" ::: "memory")
; #define PG8_BAR __builtin_amdgcn_s_barrier()
; #define PG8_SCHED __builtin_amdgcn_sched_barrier(0)
; template <class Epi, class Sched, bool ALIGN_EPI = false, bool SP2 = false>
; __device__ __forceinline__ void gemm_phase(PG8_LAS unsigned char* lds, const Gemm g, const Sched& S, const Epi& E) {
;     ...
;         for (int t = 0; t < nt; t += 2) {
;     ...
;             PG8_LDA(At, 1, 1); PG8_STAGE(PG8_SB(1, 0), b3, voffB); PG8_STAGE(PG8_SB(1, 1), b3 + hstep, voffB); PG8_STAGE(PG8_SA(1, 0), a3, voffA);
;             PG8_WAIT_V(8); PG8_WAIT_L(0); PG8_BAR; PG8_MMA(1, 0, At, B0); PG8_MMA(1, 1, At, B1); PG8_BAR; PG8_SCHED;
	s_mov_b32 m0, s31
	v_lshl_add_u64 v[210:211], v[210:211], 0, s[8:9]
	ds_read_b128 v[174:177], v140 offset:49152
	ds_read_b128 v[178:181], v140 offset:50176
	ds_read_b128 v[182:185], v140 offset:51200
	ds_read_b128 v[186:189], v140 offset:52224
	ds_read_b128 v[190:193], v140 offset:53248
	ds_read_b128 v[202:205], v140 offset:54272
	ds_read_b128 v[206:209], v140 offset:55296
	ds_read_b128 v[230:233], v140 offset:56320
	global_load_lds_dwordx4 v[210:211], off
	v_lshl_add_u64 v[210:211], v[234:235], 0, s[8:9]
	s_mov_b32 m0, s34
	s_nop 0
	global_load_lds_dwordx4 v[210:211], off
	v_lshl_add_u64 v[210:211], v[236:237], 0, s[8:9]
	s_mov_b32 m0, s65
	s_nop 0
	global_load_lds_dwordx4 v[210:211], off
	v_lshl_add_u64 v[210:211], v[238:239], 0, s[8:9]
	s_mov_b32 m0, s66
	s_nop 0
	global_load_lds_dwordx4 v[210:211], off
	v_lshl_add_u64 v[210:211], v[240:241], 0, s[8:9]
	s_mov_b32 m0, s36
	s_nop 0
	global_load_lds_dwordx4 v[210:211], off
	v_lshl_add_u64 v[210:211], v[242:243], 0, s[8:9]
	s_mov_b32 m0, s64
	s_nop 0
	global_load_lds_dwordx4 v[210:211], off
	s_waitcnt vmcnt(8)
	s_waitcnt lgkmcnt(0)
	s_barrier
	s_setprio 0
	s_waitcnt lgkmcnt(0)
	v_mfma_f32_16x16x32_bf16 v[92:95], v[142:145], v[174:177], v[92:95]
	v_mfma_f32_16x16x32_bf16 v[88:91], v[150:153], v[174:177], v[88:91]
	v_mfma_f32_16x16x32_bf16 v[84:87], v[142:145], v[182:185], v[84:87]
	v_mfma_f32_16x16x32_bf16 v[80:83], v[150:153], v[182:185], v[80:83]
	v_mfma_f32_16x16x32_bf16 v[76:79], v[142:145], v[190:193], v[76:79]
	v_mfma_f32_16x16x32_bf16 v[72:75], v[150:153], v[190:193], v[72:75]
	v_mfma_f32_16x16x32_bf16 v[12:15], v[142:145], v[206:209], v[12:15]
	v_mfma_f32_16x16x32_bf16 v[8:11], v[150:153], v[206:209], v[8:11]
	v_mfma_f32_16x16x32_bf16 v[92:95], v[146:149], v[178:181], v[92:95]
	v_mfma_f32_16x16x32_bf16 v[88:91], v[154:157], v[178:181], v[88:91]
	v_mfma_f32_16x16x32_bf16 v[84:87], v[146:149], v[186:189], v[84:87]
	v_mfma_f32_16x16x32_bf16 v[80:83], v[154:157], v[186:189], v[80:83]
	v_mfma_f32_16x16x32_bf16 v[76:79], v[146:149], v[202:205], v[76:79]
	v_mfma_f32_16x16x32_bf16 v[72:75], v[154:157], v[202:205], v[72:75]
	v_mfma_f32_16x16x32_bf16 v[12:15], v[146:149], v[230:233], v[12:15]
	v_mfma_f32_16x16x32_bf16 v[8:11], v[154:157], v[230:233], v[8:11]
	v_mfma_f32_16x16x32_bf16 v[36:39], v[158:161], v[174:177], v[36:39]
	v_mfma_f32_16x16x32_bf16 v[32:35], v[166:169], v[174:177], v[32:35]
	v_mfma_f32_16x16x32_bf16 v[28:31], v[158:161], v[182:185], v[28:31]
	v_mfma_f32_16x16x32_bf16 v[24:27], v[166:169], v[182:185], v[24:27]
	v_mfma_f32_16x16x32_bf16 v[20:23], v[158:161], v[190:193], v[20:23]
	v_mfma_f32_16x16x32_bf16 v[16:19], v[166:169], v[190:193], v[16:19]
	v_mfma_f32_16x16x32_bf16 v[4:7], v[158:161], v[206:209], v[4:7]
	v_mfma_f32_16x16x32_bf16 v[0:3], v[166:169], v[206:209], v[0:3]
	v_mfma_f32_16x16x32_bf16 v[36:39], v[162:165], v[178:181], v[36:39]
	v_mfma_f32_16x16x32_bf16 v[32:35], v[170:173], v[178:181], v[32:35]
	v_mfma_f32_16x16x32_bf16 v[28:31], v[162:165], v[186:189], v[28:31]
	v_mfma_f32_16x16x32_bf16 v[24:27], v[170:173], v[186:189], v[24:27]
	v_mfma_f32_16x16x32_bf16 v[20:23], v[162:165], v[202:205], v[20:23]
	v_mfma_f32_16x16x32_bf16 v[16:19], v[170:173], v[202:205], v[16:19]
	v_mfma_f32_16x16x32_bf16 v[4:7], v[162:165], v[230:233], v[4:7]
	v_mfma_f32_16x16x32_bf16 v[0:3], v[170:173], v[230:233], v[0:3]
	s_setprio 1
	s_barrier
	s_add_u32 s60, s60, 0x100
	s_addc_u32 s61, s61, 0
	s_add_u32 s55, s55, 0x100
	s_addc_u32 s73, s73, 0
	s_cmp_ge_i32 s74, s67
	s_mov_b32 s62, s74
	s_cbranch_scc0 .LBB0_399
	s_setprio 0
	s_and_b64 vcc, exec, s[50:51]
	s_cbranch_vccz .LBB0_410
